# c11 plus conflict-free K swizzle in cross-attention and grid-barrier leader release before its own invalidate
# baseline (speedup 1.0000x reference)
; #define LAS __attribute__((address_space(3)))
; #define GAS __attribute__((address_space(1)))
; template <int DK, int MODE> ...
;     ...
;     constexpr int PITCH = DK * 2, CPR = DK / 8, NKC = (64 * CPR) / 512, SHM_K = 64 * PITCH, ND = DK / 16;
;     LAS char* V_lds = lds; LAS char* K_lds = lds + OFF_K; LAS float* fk_l = (LAS float*)(lds + OFF_FK); LAS float* ws = (LAS float*)(lds + OFF_WS) + wid * 64;
;     bf16x8 qr[ND];
; #pragma unroll
;     for (int d0 = 0; d0 < ND; ++d0) qr[d0] = *(const GAS bf16x8*)(Qw + (size_t)r32 * qpitch + d0 * 16 + hi * 8);
;     constexpr int NKI = (64 * PITCH) / 8192;
;     const GAS bf16_t* kp[NKI]; int kstep[NKI];
; #pragma unroll
;     for (int i = 0; i < NKI; ++i) { const int off = (wid * NKI + i) * 1024 + lane * 16, row = off / PITCH, rem = off % PITCH, p = rem >> 4, ch = (p & ~7) | ((p & 7) ^ (row & 7));
;         if (DK <= 128 || ch < 16) { kp[i] = (const GAS bf16_t*)Kb + (size_t)row * kpitch + ch * 8; kstep[i] = 64 * kpitch; }
;         else { kp[i] = (const GAS bf16_t*)Kb2 + (size_t)row * k2pitch + (ch - 16) * 8; kstep[i] = 64 * k2pitch; } }
;     const GAS bf16_t* vp[2];
; #pragma unroll
;     for (int i = 0; i < 2; ++i) { const int off = (wid * 2 + i) * 1024 + lane * 16, sub = off >> 9, rem = off & 511, kk = (sub >> 2) * 8 + (rem >> 6), kq = (kk & ~0xC) | ((kk & 4) << 1) | ((kk & 8) >> 1), c = (sub & 3) * 32 + ((rem & 63) >> 1);
;         vp[i] = (const GAS bf16_t*)Vb + (size_t)kq * vpitch + c; }
;     const int vstep = 64 * vpitch;
;     ...
;     float m_reg = -1e30f, l_reg = 0.f;
; #pragma unroll
;     for (int d = 0; d < 4; ++d) o[d] = f32x16{};
;     const int vb00 = (int)(uintptr_t)V_lds + v_rd_base(lane);
;     A_LOAD(0, 0); asm volatile("s_waitcnt vmcnt(0) lgkmcnt(0)\n\ts_barrier" ::: "memory");
; __device__ __forceinline__ void ph_cross(const Args& a, char* lds, int l) {
;     ...
;         const int qb = u & 7, bh = u >> 3, b = bh >> 2, h = bh & 3; const size_t qrow = (size_t)b * SEQ + qb * 256 + wave * 32;
;         f32x16 o[4];
;         att::attn_pass<128, 2>((LAS char*)lds, QC + qrow * 512 + h * 128, 512, KVC + (size_t)b * MEMLEN * 4096 + l * 1024 + h * 128, 4096, nullptr, 0,
;                                KVC + (size_t)b * MEMLEN * 4096 + l * 1024 + 512 + h * 128, 4096, nullptr, 0.f, 4, 0, 0.08838834764831845f * LOG2E, o);
.LBB0_1611:
	s_ashr_i32 s0, s20, 5
	s_lshl_b32 s2, s20, 8
	s_ashr_i32 s1, s0, 31
	s_and_b32 s2, s2, 0x700
	s_add_u32 s6, s2, s16
	s_addc_u32 s7, 0, s17
	s_lshl_b64 s[8:9], s[0:1], 20
	s_lshl_b64 s[6:7], s[6:7], 9
	s_add_u32 s6, s6, s8
	s_addc_u32 s7, s7, s9
	s_lshl_b64 s[8:9], s[6:7], 1
	s_add_u32 s2, s12, s8
	s_addc_u32 s7, s13, s9
	s_lshl_b32 s6, s20, 4
	s_and_b32 s21, s6, 0x180
	s_lshl_b32 s10, s21, 1
	s_add_u32 s6, s2, s10
	s_addc_u32 s7, s7, 0
	s_lshl_b64 s[0:1], s[0:1], 21
	s_add_u32 s0, s18, s0
	s_addc_u32 s1, s19, s1
	s_add_u32 s0, s0, s10
	s_addc_u32 s1, s1, 0
	v_mov_b32_e32 v18, v240
	s_add_u32 s10, s0, 0x400
	s_addc_u32 s11, s1, 0
	v_readfirstlane_b32 s22, v18
	v_and_b32_e32 v20, 31, v18
	v_and_b32_e32 v19, 63, v18
	s_waitcnt lgkmcnt(0)
	v_lshlrev_b32_e32 v0, 10, v20
	v_lshrrev_b32_e32 v21, 1, v18
	s_lshl_b32 s2, s22, 5
	v_lshl_add_u64 v[2:3], s[6:7], 0, v[0:1]
	v_and_b32_e32 v148, 16, v21
	v_mov_b32_e32 v149, v1
	s_and_b32 s2, s2, 0xfffff800
	v_lshlrev_b32_e32 v22, 4, v19
	v_lshl_add_u64 v[2:3], v[2:3], 0, v[148:149]
	v_or_b32_e32 v0, s2, v22
	global_load_dwordx4 v[140:143], v[2:3], off
	global_load_dwordx4 v[136:139], v[2:3], off offset:32
	global_load_dwordx4 v[132:135], v[2:3], off offset:64
	global_load_dwordx4 v[128:131], v[2:3], off offset:96
	global_load_dwordx4 v[124:127], v[2:3], off offset:128
	global_load_dwordx4 v[120:123], v[2:3], off offset:160
	global_load_dwordx4 v[116:119], v[2:3], off offset:192
	global_load_dwordx4 v[112:115], v[2:3], off offset:224
	v_ashrrev_i32_e32 v2, 31, v0
	v_add_u32_sdwa v2, v0, v2 dst_sel:DWORD dst_unused:UNUSED_PAD src0_sel:DWORD src1_sel:BYTE_3
	v_ashrrev_i32_e32 v2, 8, v2
	s_bfe_i32 s6, s22, 0x1001a
	v_mul_i32_i24_e32 v3, 0x100, v2
	s_lshr_b32 s6, s6, 24
	v_sub_u32_e32 v3, v0, v3
	v_add_u32_e32 v0, s6, v0
	v_add_u32_e32 v0, 0x400, v0
	v_ashrrev_i32_e32 v9, 4, v3
	v_ashrrev_i32_e32 v8, 8, v0
	s_ashr_i32 s6, s2, 8
	v_bitop3_b32 v6, v2, v9, 15 bitop3:0x6c
	v_bitop3_b32 v0, v8, v9, 15 bitop3:0x6c
	v_bfe_u32 v24, v18, 2, 2
	s_and_b32 s23, s6, -16
	v_and_b32_e32 v25, 8, v21
	s_lshr_b32 s6, s6, 1
	v_ashrrev_i32_e32 v3, 31, v2
	v_lshlrev_b32_e32 v6, 3, v6
	v_lshlrev_b32_e32 v12, 3, v0
	s_and_b32 s24, s6, 4
	v_or3_b32 v0, v25, v24, s23
	v_lshlrev_b64 v[2:3], 13, v[2:3]
	v_ashrrev_i32_e32 v7, 31, v6
	v_ashrrev_i32_e32 v9, 31, v8
	v_or_b32_e32 v14, s24, v0
	v_lshl_add_u64 v[4:5], s[0:1], 0, v[2:3]
	v_lshlrev_b64 v[6:7], 1, v[6:7]
	v_lshlrev_b64 v[8:9], 13, v[8:9]
	v_ashrrev_i32_e32 v13, 31, v12
	v_lshlrev_b32_e32 v23, 3, v19
	v_and_b32_e32 v0, 32, v18
	v_ashrrev_i32_e32 v15, 31, v14
	s_add_i32 s2, s2, 0
	v_lshl_add_u64 v[4:5], v[4:5], 0, v[6:7]
	v_lshl_add_u64 v[10:11], s[0:1], 0, v[8:9]
	v_lshlrev_b64 v[12:13], 1, v[12:13]
	v_and_or_b32 v0, v23, 24, v0
	v_lshlrev_b64 v[14:15], 13, v[14:15]
	s_add_i32 m0, s2, 0x8000
	v_lshl_add_u64 v[10:11], v[10:11], 0, v[12:13]
	v_lshl_add_u64 v[14:15], s[10:11], 0, v[14:15]
	v_lshlrev_b32_e32 v0, 1, v0
	global_load_lds_dwordx4 v[4:5], off
	s_add_i32 m0, s2, 0x8400
	v_lshl_add_u64 v[14:15], v[14:15], 0, v[0:1]
	global_load_lds_dwordx4 v[10:11], off
	s_mov_b32 m0, s2
	v_lshl_add_u64 v[16:17], v[14:15], 0, s[96:97]
	global_load_lds_dwordx4 v[14:15], off
	s_add_i32 m0, s2, 0x400
	v_lshlrev_b32_e32 v4, 1, v18
	global_load_lds_dwordx4 v[16:17], off
	v_and_b32_e32 v11, 0x118, v23
	v_and_b32_e32 v5, 0xc0, v22
	v_and_or_b32 v4, v4, 32, v11
	s_and_b32 s6, s22, 0x3fffffc0
	v_lshlrev_b32_e32 v10, 4, v18
	v_add3_u32 v147, v5, 0, v4
	v_or_b32_e32 v4, s23, v25
	s_lshl_b32 s6, s6, 2
	v_and_b32_e32 v10, 0xf0, v10
	s_movk_i32 s25, 0x60
	v_or3_b32 v4, v4, s24, v24
	s_add_i32 s22, s6, 0
	v_bitop3_b32 v161, v148, v10, s25 bitop3:0x36
	s_movk_i32 s25, 0x80
	v_ashrrev_i32_e32 v5, 31, v4
	s_add_i32 s22, s22, 0x14200
	v_bitop3_b32 v160, v148, v10, s25 bitop3:0x36
	s_movk_i32 s25, 0xa0
	v_lshlrev_b64 v[4:5], 13, v[4:5]
	v_bitop3_b32 v159, v148, v10, s25 bitop3:0x36
	s_movk_i32 s25, 0xc0
	v_or_b32_e32 v4, v4, v0
	s_add_u32 s0, s0, 0x80000
	s_waitcnt vmcnt(0) lgkmcnt(0)
	s_barrier
	v_bitop3_b32 v158, v148, v10, s25 bitop3:0x36
	s_movk_i32 s25, 0xe0
	v_lshl_add_u64 v[150:151], s[10:11], 0, v[4:5]
	s_addc_u32 s1, s1, 0
	v_lshl_add_u64 v[4:5], v[8:9], 0, v[12:13]
	v_lshl_add_u64 v[2:3], v[2:3], 0, v[6:7]
	v_mov_b32_e32 v14, v1
	v_mov_b32_e32 v15, v1
	v_lshl_add_u32 v156, v20, 8, 0
	v_cmp_gt_u32_e64 s[6:7], 32, v19
	v_lshl_add_u32 v145, v20, 2, s22
	v_bitop3_b32 v164, v21, v10, 16 bitop3:0x6c
	v_bitop3_b32 v163, v148, v10, 32 bitop3:0x36
	v_bitop3_b32 v162, v148, v10, 64 bitop3:0x36
	v_bitop3_b32 v157, v148, v10, s25 bitop3:0x36
	v_lshl_add_u64 v[152:153], s[0:1], 0, v[4:5]
	v_lshl_add_u64 v[154:155], s[0:1], 0, v[2:3]
	v_mov_b32_e32 v0, v1
	v_mov_b32_e32 v2, v1
	v_mov_b32_e32 v3, v1
	v_mov_b32_e32 v4, v1
	v_mov_b32_e32 v5, v1
	v_mov_b32_e32 v6, v1
	v_mov_b32_e32 v7, v1
	v_mov_b32_e32 v8, v1
	v_mov_b32_e32 v9, v1
	v_mov_b32_e32 v10, v1
	v_mov_b32_e32 v11, v1
	v_mov_b32_e32 v12, v1
	v_mov_b32_e32 v13, v1
	v_mov_b64_e32 v[30:31], v[14:15]
	v_mov_b64_e32 v[46:47], v[14:15]
	v_mov_b64_e32 v[62:63], v[14:15]
	v_mov_b64_e32 v[78:79], v[14:15]
	s_mov_b32 s23, 0
	v_mov_b32_e32 v165, 0
	v_mov_b32_e32 v149, 0xf149f2ca
	s_mov_b64 s[0:1], 0
	v_mov_b64_e32 v[28:29], v[12:13]
	v_mov_b64_e32 v[26:27], v[10:11]
	v_mov_b64_e32 v[24:25], v[8:9]
	v_mov_b64_e32 v[22:23], v[6:7]
	v_mov_b64_e32 v[20:21], v[4:5]
	v_mov_b64_e32 v[18:19], v[2:3]
	v_mov_b64_e32 v[16:17], v[0:1]
	v_mov_b64_e32 v[44:45], v[12:13]
	v_mov_b64_e32 v[42:43], v[10:11]
	v_mov_b64_e32 v[40:41], v[8:9]
	v_mov_b64_e32 v[38:39], v[6:7]
	v_mov_b64_e32 v[36:37], v[4:5]
	v_mov_b64_e32 v[34:35], v[2:3]
	v_mov_b64_e32 v[32:33], v[0:1]
	v_mov_b64_e32 v[60:61], v[12:13]
	v_mov_b64_e32 v[58:59], v[10:11]
	v_mov_b64_e32 v[56:57], v[8:9]
	v_mov_b64_e32 v[54:55], v[6:7]
	v_mov_b64_e32 v[52:53], v[4:5]
	v_mov_b64_e32 v[50:51], v[2:3]
	v_mov_b64_e32 v[48:49], v[0:1]
	v_mov_b64_e32 v[76:77], v[12:13]
	v_mov_b64_e32 v[74:75], v[10:11]
	v_mov_b64_e32 v[72:73], v[8:9]
	v_mov_b64_e32 v[70:71], v[6:7]
	v_mov_b64_e32 v[68:69], v[4:5]
	v_mov_b64_e32 v[66:67], v[2:3]
	v_mov_b64_e32 v[64:65], v[0:1]
	s_waitcnt vmcnt(0)
